# scan operand loads: SGPR-base + 32-bit VGPR offset form (global_load_ushort v, voff, s[base]) instead of a 64-bit VALU add per load: 114 v_lshl_add_u64 dropped
# baseline (speedup 1.0000x reference)
.LBB0_704:
	s_add_i32 s42, s96, 0xffffff00
	s_lshr_b32 s46, s42, 3
	s_add_i32 s46, s46, 32
	s_lshl_b32 s52, s46, 8
	s_and_b32 s47, s96, 7
	s_lshl_b64 s[44:45], s[52:53], 11
	s_add_u32 s42, s55, s44
	s_addc_u32 s43, s57, s45
	s_lshl_b32 s52, s47, 8
	s_add_u32 s42, s42, s52
	s_addc_u32 s43, s43, 0
	global_load_ushort v28, v74, s[42:43]
	global_load_ushort v29, v100, s[42:43]
	global_load_ushort v30, v102, s[42:43]
	global_load_ushort v31, v104, s[42:43]
	global_load_ushort v32, v106, s[42:43]
	global_load_ushort v33, v108, s[42:43]
	global_load_ushort v34, v110, s[42:43]
	global_load_ushort v35, v112, s[42:43]
	global_load_ushort v36, v114, s[42:43]
	global_load_ushort v37, v116, s[42:43]
	global_load_ushort v38, v118, s[42:43]
	global_load_ushort v39, v120, s[42:43]
	global_load_ushort v40, v122, s[42:43]
	global_load_ushort v41, v124, s[42:43]
	global_load_ushort v42, v126, s[42:43]
	global_load_ushort v43, v128, s[42:43]
	v_lshl_add_u64 v[2:3], v[88:89], 0, s[44:45]
	v_lshl_add_u64 v[76:77], v[2:3], 0, s[52:53]
	v_lshl_add_u64 v[2:3], v[76:77], 0, v[124:125]
	v_mov_b32_e32 v75, v85
	v_lshl_add_u64 v[4:5], v[76:77], 0, v[126:127]
	v_lshl_add_u64 v[6:7], v[76:77], 0, v[128:129]
	global_load_ushort v84, v[2:3], off
	global_load_ushort v172, v[4:5], off
	global_load_ushort v173, v[6:7], off
	v_lshl_add_u64 v[2:3], v[76:77], 0, v[74:75]
	v_lshl_add_u64 v[4:5], v[76:77], 0, v[100:101]
	v_lshl_add_u64 v[6:7], v[76:77], 0, v[102:103]
	v_lshl_add_u64 v[8:9], v[76:77], 0, v[104:105]
	v_lshl_add_u64 v[10:11], v[76:77], 0, v[106:107]
	v_lshl_add_u64 v[12:13], v[76:77], 0, v[108:109]
	v_lshl_add_u64 v[14:15], v[76:77], 0, v[110:111]
	v_lshl_add_u64 v[16:17], v[76:77], 0, v[112:113]
	v_lshl_add_u64 v[18:19], v[76:77], 0, v[114:115]
	v_lshl_add_u64 v[20:21], v[76:77], 0, v[116:117]
	v_lshl_add_u64 v[22:23], v[76:77], 0, v[118:119]
	v_lshl_add_u64 v[24:25], v[76:77], 0, v[120:121]
	v_lshl_add_u64 v[26:27], v[76:77], 0, v[122:123]
	global_load_ushort v80, v[2:3], off
	global_load_ushort v81, v[4:5], off
	global_load_ushort v130, v[6:7], off
	global_load_ushort v131, v[8:9], off
	global_load_ushort v132, v[10:11], off
	global_load_ushort v133, v[12:13], off
	global_load_ushort v166, v[14:15], off
	global_load_ushort v167, v[16:17], off
	global_load_ushort v168, v[18:19], off
	global_load_ushort v169, v[20:21], off
	global_load_ushort v170, v[22:23], off
	global_load_ushort v171, v[24:25], off
	global_load_ushort v174, v[26:27], off
	v_and_b32_e32 v3, 64, v163
	v_xor_b32_e32 v2, 32, v163
	v_add_u32_e32 v3, 64, v3
	v_cmp_lt_i32_e32 vcc, v2, v3
	v_mov_b32_e32 v75, 0
	s_mov_b32 s52, 0
	v_cndmask_b32_e32 v2, v163, v2, vcc
	v_lshlrev_b32_e32 v79, 2, v2
	v_mov_b32_e32 v50, 0
	v_mov_b32_e32 v51, v75
	v_mov_b32_e32 v52, v75
	v_mov_b32_e32 v53, v75
	v_mov_b32_e32 v54, v75
	v_mov_b32_e32 v55, v75
	v_mov_b32_e32 v56, v75
	v_mov_b32_e32 v57, v75
	v_mov_b32_e32 v58, v75
	v_mov_b32_e32 v59, v75
	v_mov_b32_e32 v60, v75
	v_mov_b32_e32 v61, v75
	v_mov_b32_e32 v62, v75
	v_mov_b32_e32 v63, v75
	v_mov_b32_e32 v64, v75
	v_mov_b32_e32 v65, v75
	v_mov_b32_e32 v44, v75
	v_mov_b32_e32 v45, v75
	v_mov_b32_e32 v46, v75
	v_mov_b32_e32 v47, v75
	v_mov_b32_e32 v48, v75
	v_mov_b32_e32 v49, v75
	v_mov_b32_e32 v18, 0
	v_mov_b32_e32 v19, v75
	v_mov_b32_e32 v20, v75
	v_mov_b32_e32 v21, v75
	v_mov_b32_e32 v22, v75
	v_mov_b32_e32 v23, v75
	v_mov_b32_e32 v24, v75
	v_mov_b32_e32 v25, v75
	v_mov_b32_e32 v26, v75
	v_mov_b32_e32 v27, v75
	v_mov_b32_e32 v2, 0
	s_waitcnt vmcnt(0)
	v_lshl_or_b32 v66, v29, 16, v28
	v_mov_b32_e32 v28, v75
	v_lshl_or_b32 v67, v31, 16, v30
	v_mov_b32_e32 v29, v75
	v_mov_b32_e32 v30, v75
	v_lshl_or_b32 v68, v33, 16, v32
	v_mov_b32_e32 v31, v75
	v_lshl_or_b32 v69, v35, 16, v34
	v_mov_b32_e32 v34, 0
	v_mov_b32_e32 v35, v75
	v_lshl_or_b32 v70, v37, 16, v36
	v_mov_b32_e32 v36, v75
	v_lshl_or_b32 v71, v39, 16, v38
	v_mov_b32_e32 v37, v75
	v_mov_b32_e32 v38, v75
	v_lshl_or_b32 v72, v41, 16, v40
	v_mov_b32_e32 v39, v75
	v_lshl_or_b32 v73, v43, 16, v42
	v_mov_b32_e32 v40, v75
	v_mov_b32_e32 v41, v75
	v_mov_b32_e32 v42, v75
	v_mov_b32_e32 v43, v75
	v_mov_b32_e32 v32, v75
	v_mov_b32_e32 v33, v75
	v_mov_b32_e32 v3, v75
	v_mov_b32_e32 v4, v75
	v_mov_b32_e32 v5, v75
	v_mov_b32_e32 v6, v75
	v_mov_b32_e32 v7, v75
	v_mov_b32_e32 v8, v75
	v_mov_b32_e32 v9, v75
	v_mov_b32_e32 v10, v75
	v_mov_b32_e32 v11, v75
	v_mov_b32_e32 v12, v75
	v_mov_b32_e32 v13, v75
	v_mov_b32_e32 v14, v75
	v_mov_b32_e32 v15, v75
	v_mov_b32_e32 v16, v75
	v_mov_b32_e32 v17, v75
	s_branch .LBB0_707
.LBB0_705:
	s_sub_i32 s44, 6, s52
	s_add_i32 s52, s52, 1
	v_mov_b32_e32 v66, s44
	v_mov_b32_e32 v67, s52
	v_cndmask_b32_e64 v66, v66, v67, s[4:5]
	v_lshl_or_b32 v84, v66, 15, v161
	v_lshlrev_b64 v[66:67], 1, v[84:85]
	v_add_u32_e32 v84, v84, v87
	v_lshlrev_b64 v[70:71], 1, v[84:85]
	v_add_u32_e32 v84, v84, v87
	v_lshlrev_b64 v[80:81], 1, v[84:85]
	v_add_u32_e32 v84, v84, v87
	v_lshl_add_u64 v[68:69], v[76:77], 0, v[66:67]
	v_lshl_add_u64 v[130:131], v[76:77], 0, v[80:81]
	v_lshl_add_u64 v[132:133], s[42:43], 0, v[80:81]
	v_lshlrev_b64 v[80:81], 1, v[84:85]
	v_add_u32_e32 v84, v84, v87
	v_lshl_add_u64 v[72:73], v[76:77], 0, v[70:71]
	v_lshl_add_u64 v[166:167], v[76:77], 0, v[80:81]
	v_lshl_add_u64 v[168:169], s[42:43], 0, v[80:81]
	global_load_ushort v80, v[68:69], off
	global_load_ushort v78, v66, s[42:43]
	global_load_ushort v81, v[72:73], off
	global_load_ushort v184, v70, s[42:43]
	s_nop 0
	global_load_ushort v130, v[130:131], off
	s_nop 0
	global_load_ushort v185, v[132:133], off
	global_load_ushort v131, v[166:167], off
	global_load_ushort v186, v[168:169], off
	v_lshlrev_b64 v[66:67], 1, v[84:85]
	v_add_u32_e32 v84, v84, v87
	v_lshlrev_b64 v[70:71], 1, v[84:85]
	v_add_u32_e32 v84, v84, v87
	v_lshlrev_b64 v[132:133], 1, v[84:85]
	v_add_u32_e32 v84, v84, v87
	v_lshl_add_u64 v[68:69], v[76:77], 0, v[66:67]
	v_lshl_add_u64 v[166:167], v[76:77], 0, v[132:133]
	v_lshl_add_u64 v[168:169], s[42:43], 0, v[132:133]
	v_lshlrev_b64 v[132:133], 1, v[84:85]
	v_add_u32_e32 v84, v84, v87
	v_lshl_add_u64 v[72:73], v[76:77], 0, v[70:71]
	v_lshl_add_u64 v[170:171], v[76:77], 0, v[132:133]
	v_lshl_add_u64 v[172:173], s[42:43], 0, v[132:133]
	global_load_ushort v132, v[68:69], off
	global_load_ushort v187, v66, s[42:43]
	global_load_ushort v133, v[72:73], off
	global_load_ushort v188, v70, s[42:43]
	s_nop 0
	global_load_ushort v166, v[166:167], off
	s_nop 0
	global_load_ushort v189, v[168:169], off
	global_load_ushort v167, v[170:171], off
	global_load_ushort v190, v[172:173], off
	v_lshlrev_b64 v[66:67], 1, v[84:85]
	v_add_u32_e32 v84, v84, v87
	v_lshlrev_b64 v[70:71], 1, v[84:85]
	v_add_u32_e32 v84, v84, v87
	v_lshlrev_b64 v[168:169], 1, v[84:85]
	v_add_u32_e32 v84, v84, v87
	v_lshl_add_u64 v[170:171], v[76:77], 0, v[168:169]
	v_lshl_add_u64 v[172:173], s[42:43], 0, v[168:169]
	v_lshlrev_b64 v[168:169], 1, v[84:85]
	v_lshl_add_u64 v[68:69], v[76:77], 0, v[66:67]
	v_lshl_add_u64 v[174:175], v[76:77], 0, v[168:169]
	v_add_u32_e32 v84, v84, v87
	v_lshl_add_u64 v[72:73], v[76:77], 0, v[70:71]
	v_lshl_add_u64 v[176:177], s[42:43], 0, v[168:169]
	global_load_ushort v168, v[68:69], off
	global_load_ushort v191, v66, s[42:43]
	global_load_ushort v169, v[72:73], off
	global_load_ushort v192, v70, s[42:43]
	s_nop 0
	global_load_ushort v170, v[170:171], off
	s_nop 0
	global_load_ushort v193, v[172:173], off
	global_load_ushort v171, v[174:175], off
	s_nop 0
	global_load_ushort v175, v[176:177], off
	v_lshlrev_b64 v[66:67], 1, v[84:85]
	v_add_u32_e32 v84, v84, v87
	v_lshlrev_b64 v[70:71], 1, v[84:85]
	v_add_u32_e32 v84, v84, v87
	v_lshlrev_b64 v[172:173], 1, v[84:85]
	v_add_u32_e32 v84, v84, v87
	v_lshl_add_u64 v[68:69], v[76:77], 0, v[66:67]
	v_lshl_add_u64 v[72:73], v[76:77], 0, v[70:71]
	v_lshl_add_u64 v[176:177], v[76:77], 0, v[172:173]
	v_lshl_add_u64 v[178:179], s[42:43], 0, v[172:173]
	v_lshlrev_b64 v[172:173], 1, v[84:85]
	v_lshl_add_u64 v[180:181], v[76:77], 0, v[172:173]
	v_lshl_add_u64 v[182:183], s[42:43], 0, v[172:173]
	global_load_ushort v174, v[68:69], off
	global_load_ushort v194, v66, s[42:43]
	global_load_ushort v84, v[72:73], off
	s_nop 0
	global_load_ushort v72, v70, s[42:43]
	global_load_ushort v172, v[176:177], off
	global_load_ushort v73, v[178:179], off
	s_nop 0
	global_load_ushort v176, v[182:183], off
	global_load_ushort v173, v[180:181], off
	s_waitcnt vmcnt(28)
	v_lshl_or_b32 v66, v184, 16, v78
	s_waitcnt vmcnt(24)
	v_lshl_or_b32 v67, v186, 16, v185
	s_waitcnt vmcnt(20)
	v_lshl_or_b32 v68, v188, 16, v187
	s_waitcnt vmcnt(16)
	v_lshl_or_b32 v69, v190, 16, v189
	s_waitcnt vmcnt(12)
	v_lshl_or_b32 v70, v192, 16, v191
	s_waitcnt vmcnt(8)
	v_lshl_or_b32 v71, v175, 16, v193
	s_waitcnt vmcnt(4)
	v_lshl_or_b32 v72, v72, 16, v194
	s_waitcnt vmcnt(1)
	v_lshl_or_b32 v73, v176, 16, v73

.LBB0_714:
	s_ashr_i32 s46, s96, 3
	s_lshl_b32 s58, s46, 8
	s_and_b32 s47, s96, 7
	s_ashr_i32 s59, s58, 31
	s_lshl_b32 s97, s47, 7
	s_lshl_b64 s[42:43], s[58:59], 11
	s_add_u32 s44, s76, s42
	s_addc_u32 s45, s77, s43
	s_lshl_b32 s52, s47, 8
	s_add_u32 s60, s44, s52
	s_addc_u32 s61, s45, 0
	s_add_u32 s44, s55, s42
	s_addc_u32 s45, s57, s43
	s_add_u32 s62, s44, s52
	s_addc_u32 s63, s45, 0
	global_load_ushort v48, v74, s[62:63]
	global_load_ushort v49, v100, s[62:63]
	global_load_ushort v50, v102, s[62:63]
	global_load_ushort v51, v104, s[62:63]
	global_load_ushort v52, v106, s[62:63]
	global_load_ushort v53, v108, s[62:63]
	global_load_ushort v54, v110, s[62:63]
	global_load_ushort v55, v112, s[62:63]
	global_load_ushort v56, v114, s[62:63]
	global_load_ushort v57, v116, s[62:63]
	global_load_ushort v58, v118, s[62:63]
	global_load_ushort v59, v120, s[62:63]
	global_load_ushort v60, v122, s[62:63]
	global_load_ushort v61, v124, s[62:63]
	global_load_ushort v62, v126, s[62:63]
	global_load_ushort v63, v128, s[62:63]
	v_lshl_add_u64 v[2:3], v[88:89], 0, s[42:43]
	v_lshl_add_u64 v[130:131], v[2:3], 0, s[52:53]
	v_mov_b32_e32 v75, v85
	v_lshl_add_u64 v[2:3], v[130:131], 0, v[106:107]
	v_lshl_add_u64 v[4:5], v[130:131], 0, v[108:109]
	v_lshl_add_u64 v[6:7], v[130:131], 0, v[122:123]
	v_lshl_add_u64 v[8:9], v[130:131], 0, v[124:125]
	v_lshl_add_u64 v[10:11], v[130:131], 0, v[126:127]
	v_lshl_add_u64 v[12:13], v[130:131], 0, v[128:129]
	v_lshl_add_u64 v[14:15], v[130:131], 0, v[74:75]
	v_lshl_add_u64 v[16:17], v[130:131], 0, v[100:101]
	v_lshl_add_u64 v[18:19], v[130:131], 0, v[102:103]
	v_lshl_add_u64 v[20:21], v[130:131], 0, v[104:105]
	global_load_ushort v187, v[2:3], off
	global_load_ushort v188, v[4:5], off
	global_load_ushort v180, v108, s[60:61]
	global_load_ushort v173, v106, s[60:61]
	global_load_ushort v177, v104, s[60:61]
	global_load_ushort v194, v[6:7], off
	global_load_ushort v195, v[8:9], off
	global_load_ushort v171, v124, s[60:61]
	global_load_ushort v168, v122, s[60:61]
	global_load_ushort v170, v120, s[60:61]
	global_load_ushort v201, v[10:11], off
	global_load_ushort v182, v74, s[60:61]
	global_load_ushort v202, v[12:13], off
	global_load_ushort v84, v128, s[60:61]
	global_load_ushort v169, v126, s[60:61]
	global_load_ushort v184, v[14:15], off
	global_load_ushort v185, v[16:17], off
	global_load_ushort v186, v[18:19], off
	global_load_ushort v190, v[20:21], off
	global_load_ushort v178, v102, s[60:61]
	global_load_ushort v181, v100, s[60:61]
	v_lshl_add_u64 v[22:23], v[130:131], 0, v[110:111]
	v_lshl_add_u64 v[24:25], v[130:131], 0, v[112:113]
	v_lshl_add_u64 v[4:5], v[130:131], 0, v[114:115]
	global_load_ushort v192, v[22:23], off
	global_load_ushort v193, v[24:25], off
	global_load_ushort v196, v[4:5], off
	global_load_ushort v175, v114, s[60:61]
	global_load_ushort v176, v112, s[60:61]
	global_load_ushort v179, v110, s[60:61]
	v_lshl_add_u64 v[2:3], v[130:131], 0, v[116:117]
	v_lshl_add_u64 v[6:7], v[130:131], 0, v[118:119]
	v_lshl_add_u64 v[10:11], v[130:131], 0, v[120:121]
	global_load_ushort v197, v[2:3], off
	global_load_ushort v198, v[6:7], off
	global_load_ushort v199, v[10:11], off
	global_load_ushort v172, v118, s[60:61]
	global_load_ushort v174, v116, s[60:61]
	v_and_b32_e32 v3, 64, v163
	v_xor_b32_e32 v2, 32, v163
	v_add_u32_e32 v166, 64, v3
	v_cmp_lt_i32_e32 vcc, v2, v166
	v_mov_b32_e32 v34, 0
	s_mov_b32 s59, 0
	v_cndmask_b32_e32 v2, v163, v2, vcc
	v_lshlrev_b32_e32 v167, 2, v2
	s_mov_b32 s52, 6
	v_mov_b32_e32 v35, v34
	v_mov_b32_e32 v36, v34
	v_mov_b32_e32 v37, v34
	v_mov_b32_e32 v38, v34
	v_mov_b32_e32 v39, v34
	v_mov_b32_e32 v40, v34
	v_mov_b32_e32 v41, v34
	v_mov_b32_e32 v42, v34
	v_mov_b32_e32 v43, v34
	v_mov_b32_e32 v44, v34
	v_mov_b32_e32 v45, v34
	v_mov_b32_e32 v46, v34
	v_mov_b32_e32 v47, v34
	v_mov_b32_e32 v64, v34
	s_waitcnt vmcnt(0)
	v_lshl_or_b32 v66, v49, 16, v48
	v_mov_b32_e32 v48, v34
	v_mov_b32_e32 v49, v34
	v_lshl_or_b32 v67, v51, 16, v50
	v_mov_b32_e32 v50, v34
	v_lshl_or_b32 v68, v53, 16, v52
	v_mov_b32_e32 v51, v34
	v_mov_b32_e32 v52, v34
	v_lshl_or_b32 v69, v55, 16, v54
	v_mov_b32_e32 v53, v34
	v_mov_b32_e32 v54, v34
	v_lshl_or_b32 v70, v57, 16, v56
	v_mov_b32_e32 v55, v34
	v_mov_b32_e32 v56, v34
	v_lshl_or_b32 v71, v59, 16, v58
	v_mov_b32_e32 v57, v34
	v_lshl_or_b32 v72, v61, 16, v60
	v_mov_b32_e32 v58, v34
	v_mov_b32_e32 v59, v34
	v_lshl_or_b32 v73, v63, 16, v62
	v_mov_b32_e32 v60, v34
	v_mov_b32_e32 v61, v34
	v_mov_b32_e32 v62, v34
	v_mov_b32_e32 v63, v34
	v_mov_b32_e32 v65, v34
	v_mov_b32_e32 v18, v34
	v_mov_b32_e32 v19, v34
	v_mov_b32_e32 v20, v34
	v_mov_b32_e32 v21, v34
	v_mov_b32_e32 v22, v34
	v_mov_b32_e32 v23, v34
	v_mov_b32_e32 v24, v34
	v_mov_b32_e32 v25, v34
	v_mov_b32_e32 v26, v34
	v_mov_b32_e32 v27, v34
	v_mov_b32_e32 v28, v34
	v_mov_b32_e32 v29, v34
	v_mov_b32_e32 v30, v34
	v_mov_b32_e32 v31, v34
	v_mov_b32_e32 v32, v34
	v_mov_b32_e32 v33, v34
	v_mov_b32_e32 v2, v34
	v_mov_b32_e32 v3, v34
	v_mov_b32_e32 v4, v34
	v_mov_b32_e32 v5, v34
	v_mov_b32_e32 v6, v34
	v_mov_b32_e32 v7, v34
	v_mov_b32_e32 v8, v34
	v_mov_b32_e32 v9, v34
	v_mov_b32_e32 v10, v34
	v_mov_b32_e32 v11, v34
	v_mov_b32_e32 v12, v34
	v_mov_b32_e32 v13, v34
	v_mov_b32_e32 v14, v34
	v_mov_b32_e32 v15, v34
	v_mov_b32_e32 v16, v34
	v_mov_b32_e32 v17, v34
.LBB0_715:
	v_cvt_f32_f16_e32 v75, v184
	v_cvt_f32_f16_e32 v77, v185
	v_cvt_f32_f16_e32 v80, v186
	v_cvt_f32_f16_e32 v81, v190
	v_add_f32_e32 v74, 0, v75
	v_cvt_f32_f16_e32 v183, v187
	v_add_f32_e32 v79, v74, v77
	v_cvt_f32_f16_e32 v184, v188
	v_add_f32_e32 v132, v79, v80
	v_cvt_f32_f16_e32 v185, v192
	v_add_f32_e32 v133, v132, v81
	v_cvt_f32_f16_e32 v186, v193
	v_add_f32_e32 v187, v133, v183
	v_cvt_f32_f16_e32 v191, v196
	v_add_f32_e32 v188, v187, v184
	v_cvt_f32_f16_e32 v192, v197
	v_add_f32_e32 v189, v188, v185
	v_cvt_f32_f16_e32 v193, v198
	v_add_f32_e32 v190, v189, v186
	v_cvt_f32_f16_e32 v196, v199
	v_add_f32_e32 v197, v190, v191
	v_cvt_f32_f16_e32 v194, v194
	v_add_f32_e32 v198, v197, v192
	v_cvt_f32_f16_e32 v195, v195
	v_add_f32_e32 v199, v198, v193
	v_cvt_f32_f16_e32 v201, v201
	v_add_f32_e32 v200, v199, v196
	v_cvt_f32_f16_e32 v202, v202
	v_add_f32_e32 v203, v200, v194
	v_add_f32_e32 v204, v203, v195
	v_add_f32_e32 v205, v204, v201
	v_add_f32_e32 v206, v205, v202
	ds_bpermute_b32 v76, v167, v206
	v_mul_f32_e32 v75, 0x3fb8aa3b, v75
	v_lshlrev_b32_e32 v172, 16, v172
	v_lshlrev_b32_e32 v168, 16, v168
	v_lshlrev_b32_e32 v169, 16, v169
	s_waitcnt lgkmcnt(0)
	v_cndmask_b32_e64 v207, v76, 0, s[6:7]
	v_add_f32_e32 v74, v74, v207
	v_mul_f32_e32 v74, 0x3fb8aa3b, v74
	v_exp_f32_e32 v208, v74
	v_add_f32_e32 v79, v79, v207
	v_add_f32_e32 v78, v206, v76
	v_exp_f32_e32 v76, v75
	v_lshlrev_b32_e32 v75, 16, v182
	v_mul_f32_e32 v79, 0x3fb8aa3b, v79
	v_mul_f32_e32 v75, v208, v75
	v_exp_f32_e32 v182, v79
	v_cvt_pk_bf16_f32 v75, v75, s0
	ds_write_b16 v164, v75
	v_mul_f32_e32 v75, 0x3fb8aa3b, v77
	v_mul_f32_e32 v78, 0x3fb8aa3b, v78
	v_exp_f32_e32 v77, v75
	v_exp_f32_e32 v74, v78
	v_rcp_f32_e32 v78, v208
	v_rcp_f32_e32 v79, v182
	v_lshlrev_b32_e32 v75, 16, v181
	v_mul_f32_e32 v75, v182, v75
	v_pk_add_f32 v[76:77], v[76:77], 1.0 op_sel_hi:[1,0] neg_lo:[1,0] neg_hi:[1,0]
	v_cvt_pk_bf16_f32 v75, v75, s0
	v_pk_mul_f32 v[76:77], v[76:77], v[78:79]
	ds_write_b16 v164, v75 offset:272
	v_cvt_pk_bf16_f32 v75, v76, s0
	ds_write_b16 v164, v75 offset:8704
	v_cvt_pk_bf16_f32 v75, v77, s0
	ds_write_b16 v164, v75 offset:8976
	v_add_f32_e32 v75, v132, v207
	v_mul_f32_e32 v75, 0x3fb8aa3b, v75
	v_exp_f32_e32 v75, v75
	v_lshlrev_b32_e32 v79, 16, v178
	v_mul_f32_e32 v78, 0x3fb8aa3b, v80
	v_exp_f32_e32 v78, v78
	v_pk_mul_f32 v[76:77], v[74:75], v[76:77] op_sel_hi:[0,1]
	v_rcp_f32_e32 v80, v75
	v_mul_f32_e32 v75, v75, v79
	v_add_f32_e32 v79, v133, v207
	v_mul_f32_e32 v79, 0x3fb8aa3b, v79
	v_exp_f32_e32 v132, v79
	v_cvt_pk_bf16_f32 v75, v75, s0
	ds_write_b16 v164, v75 offset:544
	v_mul_f32_e32 v75, 0x3fb8aa3b, v81
	v_exp_f32_e32 v79, v75
	v_rcp_f32_e32 v81, v132
	v_lshlrev_b32_e32 v75, 16, v177
	v_mul_f32_e32 v75, v132, v75
	v_pk_add_f32 v[78:79], v[78:79], 1.0 op_sel_hi:[1,0] neg_lo:[1,0] neg_hi:[1,0]
	v_cvt_pk_bf16_f32 v75, v75, s0
	v_pk_mul_f32 v[78:79], v[78:79], v[80:81]
	ds_write_b16 v164, v75 offset:816
	v_cvt_pk_bf16_f32 v75, v78, s0
	ds_write_b16 v164, v75 offset:9248
	v_cvt_pk_bf16_f32 v75, v79, s0
	ds_write_b16 v164, v75 offset:9520
	v_add_f32_e32 v75, v187, v207
	v_mul_f32_e32 v75, 0x3fb8aa3b, v75
	v_exp_f32_e32 v75, v75
	v_lshlrev_b32_e32 v81, 16, v173
	v_mul_f32_e32 v80, 0x3fb8aa3b, v183
	v_exp_f32_e32 v80, v80
	v_pk_mul_f32 v[78:79], v[74:75], v[78:79] op_sel_hi:[0,1]
	v_rcp_f32_e32 v132, v75
	v_mul_f32_e32 v75, v75, v81
	v_add_f32_e32 v81, v188, v207
	v_mul_f32_e32 v81, 0x3fb8aa3b, v81
	v_exp_f32_e32 v173, v81
	v_cvt_pk_bf16_f32 v75, v75, s0
	ds_write_b16 v164, v75 offset:1088
	v_mul_f32_e32 v75, 0x3fb8aa3b, v184
	v_exp_f32_e32 v81, v75
	v_rcp_f32_e32 v133, v173
	v_lshlrev_b32_e32 v75, 16, v180
	v_mul_f32_e32 v75, v173, v75
	v_pk_add_f32 v[80:81], v[80:81], 1.0 op_sel_hi:[1,0] neg_lo:[1,0] neg_hi:[1,0]
	v_cvt_pk_bf16_f32 v75, v75, s0
	v_pk_mul_f32 v[80:81], v[80:81], v[132:133]
	ds_write_b16 v164, v75 offset:1360
	v_cvt_pk_bf16_f32 v75, v80, s0
	ds_write_b16 v164, v75 offset:9792
	v_cvt_pk_bf16_f32 v75, v81, s0
	ds_write_b16 v164, v75 offset:10064
	v_add_f32_e32 v75, v189, v207
	v_mul_f32_e32 v75, 0x3fb8aa3b, v75
	v_exp_f32_e32 v75, v75
	v_lshlrev_b32_e32 v133, 16, v179
	v_mul_f32_e32 v132, 0x3fb8aa3b, v185
	v_exp_f32_e32 v132, v132
	v_pk_mul_f32 v[80:81], v[74:75], v[80:81] op_sel_hi:[0,1]
	v_rcp_f32_e32 v178, v75
	v_mul_f32_e32 v75, v75, v133
	v_add_f32_e32 v133, v190, v207
	v_mul_f32_e32 v133, 0x3fb8aa3b, v133
	v_exp_f32_e32 v173, v133
	v_cvt_pk_bf16_f32 v75, v75, s0
	ds_write_b16 v164, v75 offset:1632
	v_mul_f32_e32 v75, 0x3fb8aa3b, v186
	v_exp_f32_e32 v133, v75
	v_rcp_f32_e32 v179, v173
	v_lshlrev_b32_e32 v75, 16, v176
	v_mul_f32_e32 v75, v173, v75
	v_pk_add_f32 v[132:133], v[132:133], 1.0 op_sel_hi:[1,0] neg_lo:[1,0] neg_hi:[1,0]
	v_cvt_pk_bf16_f32 v75, v75, s0
	v_pk_mul_f32 v[132:133], v[132:133], v[178:179]
	ds_write_b16 v164, v75 offset:1904
	v_cvt_pk_bf16_f32 v75, v132, s0
	ds_write_b16 v164, v75 offset:10336
	v_cvt_pk_bf16_f32 v75, v133, s0
	ds_write_b16 v164, v75 offset:10608
	v_add_f32_e32 v75, v197, v207
	v_mul_f32_e32 v75, 0x3fb8aa3b, v75
	v_exp_f32_e32 v75, v75
	v_mul_f32_e32 v173, 0x3fb8aa3b, v191
	v_exp_f32_e32 v176, v173
	v_lshlrev_b32_e32 v173, 16, v175
	v_pk_mul_f32 v[132:133], v[74:75], v[132:133] op_sel_hi:[0,1]
	v_rcp_f32_e32 v178, v75
	v_mul_f32_e32 v75, v75, v173
	v_add_f32_e32 v173, v198, v207
	v_mul_f32_e32 v173, 0x3fb8aa3b, v173
	v_exp_f32_e32 v173, v173
	v_cvt_pk_bf16_f32 v75, v75, s0
	ds_write_b16 v164, v75 offset:2176
	v_mul_f32_e32 v75, 0x3fb8aa3b, v192
	v_exp_f32_e32 v177, v75
	v_rcp_f32_e32 v179, v173
	v_lshlrev_b32_e32 v75, 16, v174
	v_mul_f32_e32 v75, v173, v75
	v_pk_add_f32 v[174:175], v[176:177], 1.0 op_sel_hi:[1,0] neg_lo:[1,0] neg_hi:[1,0]
	v_cvt_pk_bf16_f32 v75, v75, s0
	v_pk_mul_f32 v[174:175], v[174:175], v[178:179]
	ds_write_b16 v164, v75 offset:2448
	v_cvt_pk_bf16_f32 v75, v174, s0
	ds_write_b16 v164, v75 offset:10880
	v_cvt_pk_bf16_f32 v75, v175, s0
	ds_write_b16 v164, v75 offset:11152
	v_add_f32_e32 v75, v199, v207
	v_mul_f32_e32 v75, 0x3fb8aa3b, v75
	v_exp_f32_e32 v75, v75
	v_mul_f32_e32 v173, 0x3fb8aa3b, v193
	v_exp_f32_e32 v176, v173
	v_cvt_pk_bf16_f32 v76, v76, v77
	v_pk_mul_f32 v[174:175], v[74:75], v[174:175] op_sel_hi:[0,1]
	v_rcp_f32_e32 v178, v75
	v_mul_f32_e32 v75, v75, v172
	v_add_f32_e32 v172, v200, v207
	v_mul_f32_e32 v172, 0x3fb8aa3b, v172
	v_exp_f32_e32 v172, v172
	v_cvt_pk_bf16_f32 v75, v75, s0
	ds_write_b16 v164, v75 offset:2720
	v_mul_f32_e32 v75, 0x3fb8aa3b, v196
	v_exp_f32_e32 v177, v75
	v_rcp_f32_e32 v179, v172
	v_lshlrev_b32_e32 v75, 16, v170
	v_mul_f32_e32 v75, v172, v75
	v_pk_add_f32 v[172:173], v[176:177], 1.0 op_sel_hi:[1,0] neg_lo:[1,0] neg_hi:[1,0]
	v_cvt_pk_bf16_f32 v75, v75, s0
	v_pk_mul_f32 v[172:173], v[172:173], v[178:179]
	ds_write_b16 v164, v75 offset:2992
	v_cvt_pk_bf16_f32 v75, v172, s0
	ds_write_b16 v164, v75 offset:11424
	v_cvt_pk_bf16_f32 v75, v173, s0
	ds_write_b16 v164, v75 offset:11696
	v_add_f32_e32 v75, v203, v207
	v_mul_f32_e32 v75, 0x3fb8aa3b, v75
	v_exp_f32_e32 v75, v75
	v_mul_f32_e32 v170, 0x3fb8aa3b, v194
	v_exp_f32_e32 v176, v170
	v_cvt_pk_bf16_f32 v77, v78, v79
	v_pk_mul_f32 v[172:173], v[74:75], v[172:173] op_sel_hi:[0,1]
	v_rcp_f32_e32 v178, v75
	v_mul_f32_e32 v75, v75, v168
	v_add_f32_e32 v168, v204, v207
	v_mul_f32_e32 v168, 0x3fb8aa3b, v168
	v_exp_f32_e32 v168, v168
	v_cvt_pk_bf16_f32 v75, v75, s0
	ds_write_b16 v164, v75 offset:3264
	v_mul_f32_e32 v75, 0x3fb8aa3b, v195
	v_exp_f32_e32 v177, v75
	v_rcp_f32_e32 v179, v168
	v_lshlrev_b32_e32 v75, 16, v171
	v_mul_f32_e32 v75, v168, v75
	v_pk_add_f32 v[170:171], v[176:177], 1.0 op_sel_hi:[1,0] neg_lo:[1,0] neg_hi:[1,0]
	v_cvt_pk_bf16_f32 v75, v75, s0
	v_pk_mul_f32 v[170:171], v[170:171], v[178:179]
	ds_write_b16 v164, v75 offset:3536
	v_cvt_pk_bf16_f32 v75, v170, s0
	ds_write_b16 v164, v75 offset:11968
	v_cvt_pk_bf16_f32 v75, v171, s0
	ds_write_b16 v164, v75 offset:12240
	v_add_f32_e32 v75, v205, v207
	v_mul_f32_e32 v75, 0x3fb8aa3b, v75
	v_exp_f32_e32 v75, v75
	v_mul_f32_e32 v168, 0x3fb8aa3b, v201
	v_exp_f32_e32 v168, v168
	v_cvt_pk_bf16_f32 v78, v80, v81
	v_pk_mul_f32 v[170:171], v[74:75], v[170:171] op_sel_hi:[0,1]
	v_rcp_f32_e32 v176, v75
	v_mul_f32_e32 v75, v75, v169
	v_add_f32_e32 v169, v206, v207
	v_mul_f32_e32 v169, 0x3fb8aa3b, v169
	v_exp_f32_e32 v178, v169
	v_cvt_pk_bf16_f32 v75, v75, s0
	ds_write_b16 v164, v75 offset:3808
	v_mul_f32_e32 v75, 0x3fb8aa3b, v202
	v_exp_f32_e32 v169, v75
	v_rcp_f32_e32 v177, v178
	v_lshlrev_b32_e32 v75, 16, v84
	v_mul_f32_e32 v75, v178, v75
	v_pk_add_f32 v[168:169], v[168:169], 1.0 op_sel_hi:[1,0] neg_lo:[1,0] neg_hi:[1,0]
	v_cvt_pk_bf16_f32 v75, v75, s0
	v_pk_mul_f32 v[168:169], v[168:169], v[176:177]
	ds_write_b16 v164, v75 offset:4080
	v_cvt_pk_bf16_f32 v75, v168, s0
	ds_write_b16 v164, v75 offset:12512
	v_cvt_pk_bf16_f32 v75, v169, s0
	v_pk_mul_f32 v[176:177], v[74:75], v[168:169] op_sel_hi:[0,1]
	v_cvt_pk_bf16_f32 v79, v132, v133
	v_add_u32_e32 v183, v135, v136
	ds_write_b16 v164, v75 offset:12784
	v_cvt_pk_bf16_f32 v168, v174, v175
	v_cvt_pk_bf16_f32 v169, v172, v173
	v_cvt_pk_bf16_f32 v170, v170, v171
	v_cvt_pk_bf16_f32 v171, v176, v177
	ds_write_b128 v183, v[76:79] offset:17408
	ds_write_b128 v183, v[168:171] offset:17424
	ds_write_b128 v183, v[66:69] offset:27648
	ds_write_b128 v183, v[70:73] offset:27664
	s_and_saveexec_b64 s[42:43], s[6:7]
	v_add_u32_e32 v66, v135, v138
	ds_write_b32 v66, v74 offset:37888
	s_or_b64 exec, exec, s[42:43]
	s_add_i32 s44, s59, 1
	v_mov_b32_e32 v66, s52
	v_mov_b32_e32 v67, s44
	v_cndmask_b32_e64 v66, v66, v67, s[4:5]
	v_lshl_or_b32 v84, v66, 15, v161
	v_lshlrev_b64 v[66:67], 1, v[84:85]
	v_add_u32_e32 v84, v84, v87
	v_lshlrev_b64 v[72:73], 1, v[84:85]
	v_add_u32_e32 v84, v84, v87
	v_lshl_add_u64 v[68:69], v[130:131], 0, v[66:67]
	v_lshlrev_b64 v[78:79], 1, v[84:85]
	v_add_u32_e32 v84, v84, v87
	s_waitcnt lgkmcnt(0)
	s_barrier
	v_lshl_add_u64 v[74:75], v[130:131], 0, v[72:73]
	v_lshl_add_u64 v[80:81], v[130:131], 0, v[78:79]
	global_load_ushort v184, v[68:69], off
	global_load_ushort v182, v66, s[60:61]
	global_load_ushort v203, v66, s[62:63]
	global_load_ushort v185, v[74:75], off
	global_load_ushort v181, v72, s[60:61]
	global_load_ushort v204, v72, s[62:63]
	global_load_ushort v186, v[80:81], off
	global_load_ushort v178, v78, s[60:61]
	v_lshlrev_b64 v[68:69], 1, v[84:85]
	v_add_u32_e32 v84, v84, v87
	v_lshlrev_b64 v[74:75], 1, v[84:85]
	v_add_u32_e32 v84, v84, v87
	v_lshlrev_b64 v[80:81], 1, v[84:85]
	v_add_u32_e32 v84, v84, v87
	v_lshl_add_u64 v[70:71], v[130:131], 0, v[68:69]
	v_lshl_add_u64 v[76:77], v[130:131], 0, v[74:75]
	v_lshl_add_u64 v[132:133], v[130:131], 0, v[80:81]
	global_load_ushort v205, v78, s[62:63]
	global_load_ushort v190, v[70:71], off
	global_load_ushort v177, v68, s[60:61]
	global_load_ushort v207, v68, s[62:63]
	global_load_ushort v187, v[76:77], off
	global_load_ushort v173, v74, s[60:61]
	global_load_ushort v206, v74, s[62:63]
	global_load_ushort v188, v[132:133], off
	v_lshlrev_b64 v[66:67], 1, v[84:85]
	v_add_u32_e32 v84, v84, v87
	v_lshl_add_u64 v[74:75], v[130:131], 0, v[66:67]
	v_lshl_add_u64 v[76:77], s[60:61], 0, v[66:67]
	v_lshl_add_u64 v[78:79], s[62:63], 0, v[66:67]
	v_lshlrev_b64 v[66:67], 1, v[84:85]
	v_add_u32_e32 v191, v140, v134
	v_lshl_add_u64 v[70:71], s[60:61], 0, v[80:81]
	v_lshl_add_u64 v[72:73], s[62:63], 0, v[80:81]
	v_lshl_add_u64 v[80:81], v[130:131], 0, v[66:67]
	v_lshl_add_u64 v[132:133], s[60:61], 0, v[66:67]
	v_lshl_add_u64 v[168:169], s[62:63], 0, v[66:67]
	ds_read_b128 v[66:69], v191 offset:8704
	global_load_ushort v180, v[70:71], off
	global_load_ushort v209, v[72:73], off
	global_load_ushort v192, v[74:75], off
	global_load_ushort v179, v[76:77], off
	global_load_ushort v208, v[78:79], off
	global_load_ushort v193, v[80:81], off
	global_load_ushort v176, v[132:133], off
	global_load_ushort v210, v[168:169], off
	ds_read_b128 v[70:73], v165
	s_waitcnt lgkmcnt(0)
	v_mfma_f32_32x32x16_bf16 v[66:81], v[66:69], v[70:73], 0
	ds_read_b128 v[168:171], v191 offset:8736
	ds_read_b128 v[194:197], v165 offset:32
	v_add_u32_e32 v84, v84, v87
	v_lshlrev_b64 v[132:133], 1, v[84:85]
	v_add_u32_e32 v84, v84, v87
	v_lshlrev_b64 v[198:199], 1, v[84:85]
	v_lshl_add_u64 v[222:223], v[130:131], 0, v[198:199]
	v_lshl_add_u64 v[224:225], s[60:61], 0, v[198:199]
	v_lshl_add_u64 v[226:227], s[62:63], 0, v[198:199]
	ds_read_b128 v[198:201], v191 offset:8768
	s_waitcnt lgkmcnt(1)
	v_mfma_f32_32x32x16_bf16 v[66:81], v[168:171], v[194:197], v[66:81]
	ds_read_b128 v[168:171], v165 offset:64
	ds_read_b128 v[214:217], v191 offset:8800
	ds_read_b128 v[218:221], v165 offset:96
	v_add_u32_e32 v84, v84, v87
	v_lshl_add_u64 v[174:175], v[130:131], 0, v[132:133]
	v_lshlrev_b64 v[194:195], 1, v[84:85]
	s_waitcnt lgkmcnt(2)
	v_mfma_f32_32x32x16_bf16 v[66:81], v[198:201], v[168:171], v[66:81]
	v_lshl_add_u64 v[228:229], v[130:131], 0, v[194:195]
	global_load_ushort v196, v[174:175], off
	s_nop 0
	global_load_ushort v175, v132, s[60:61]
	global_load_ushort v211, v132, s[62:63]
	global_load_ushort v197, v[222:223], off
	global_load_ushort v174, v[224:225], off
	s_nop 0
	global_load_ushort v212, v[226:227], off
	global_load_ushort v198, v[228:229], off
	global_load_ushort v172, v194, s[60:61]
	ds_read_b128 v[168:171], v191 offset:8832
	v_add_u32_e32 v84, v84, v87
	v_lshl_add_u64 v[132:133], s[62:63], 0, v[194:195]
	v_lshlrev_b64 v[194:195], 1, v[84:85]
	s_waitcnt lgkmcnt(1)
	v_mfma_f32_32x32x16_bf16 v[66:81], v[214:217], v[218:221], v[66:81]
	ds_read_b128 v[214:217], v165 offset:128
	ds_read_b128 v[218:221], v191 offset:8864
	ds_read_b128 v[222:225], v165 offset:160
	v_add_u32_e32 v84, v84, v87
	v_lshl_add_u64 v[200:201], v[130:131], 0, v[194:195]
	s_add_i32 s42, s52, 1
	s_waitcnt lgkmcnt(2)
	v_mfma_f32_32x32x16_bf16 v[66:81], v[168:171], v[214:217], v[66:81]
	v_lshlrev_b64 v[168:169], 1, v[84:85]
	v_add_u32_e32 v84, v84, v87
	v_lshl_add_u64 v[228:229], v[130:131], 0, v[168:169]
	v_lshlrev_b64 v[234:235], 1, v[84:85]
	v_lshl_add_u64 v[232:233], s[62:63], 0, v[168:169]
	v_lshl_add_u64 v[236:237], v[130:131], 0, v[234:235]
	s_waitcnt lgkmcnt(0)
	v_mfma_f32_32x32x16_bf16 v[66:81], v[218:221], v[222:225], v[66:81]
	ds_read_b128 v[216:219], v191 offset:8896
	ds_read_b128 v[220:223], v165 offset:192
	global_load_ushort v213, v[132:133], off
	global_load_ushort v199, v[200:201], off
	global_load_ushort v170, v194, s[60:61]
	global_load_ushort v215, v194, s[62:63]
	s_nop 0
	global_load_ushort v194, v[228:229], off
	global_load_ushort v168, v168, s[60:61]
	global_load_ushort v214, v[232:233], off
	global_load_ushort v195, v[236:237], off
	ds_read_b128 v[224:227], v191 offset:8928
	ds_read_b128 v[228:231], v165 offset:224
	v_add_u32_e32 v84, v84, v87
	v_lshlrev_b64 v[200:201], 1, v[84:85]
	v_lshl_add_u64 v[132:133], s[60:61], 0, v[234:235]
	v_lshl_add_u64 v[232:233], s[62:63], 0, v[234:235]
	s_waitcnt lgkmcnt(2)
	v_mfma_f32_32x32x16_bf16 v[66:81], v[216:219], v[220:223], v[66:81]
	v_lshl_add_u64 v[234:235], v[130:131], 0, v[200:201]
	v_lshl_add_u64 v[236:237], s[60:61], 0, v[200:201]
	v_lshl_add_u64 v[238:239], s[62:63], 0, v[200:201]
	v_add_u32_e32 v84, v84, v87
	s_waitcnt lgkmcnt(0)
	v_mfma_f32_32x32x16_bf16 v[66:81], v[224:227], v[228:231], v[66:81]
	s_nop 11
	v_cndmask_b32_e64 v169, v66, 0, s[8:9]
	v_cndmask_b32_e64 v66, v169, v66, s[10:11]
	v_cndmask_b32_e64 v67, 0, v67, s[10:11]
	v_cndmask_b32_e64 v68, v68, 0, s[12:13]
	v_cndmask_b32_e64 v69, v69, 0, s[14:15]
	v_cndmask_b32_e64 v70, v70, 0, s[16:17]
	v_cndmask_b32_e64 v71, v71, 0, s[18:19]
	v_cvt_pk_bf16_f32 v66, v66, v67
	v_cvt_pk_bf16_f32 v67, v68, v69
	v_cvt_pk_bf16_f32 v68, v70, v71
	v_add_u32_e32 v70, v135, v141
	v_cndmask_b32_e64 v72, v72, 0, s[20:21]
	v_cndmask_b32_e64 v73, v73, 0, s[22:23]
	v_add_u32_e32 v200, 0x6800, v70
	v_cvt_pk_bf16_f32 v69, v72, v73
	ds_read2_b64 v[70:73], v200 offset0:128 offset1:130
	v_cndmask_b32_e64 v169, v74, 0, s[24:25]
	v_cndmask_b32_e64 v171, v75, 0, s[26:27]
	v_cndmask_b32_e64 v189, v76, 0, s[28:29]
	v_cndmask_b32_e64 v201, v77, 0, s[30:31]
	v_cndmask_b32_e64 v202, v78, 0, s[34:35]
	v_cndmask_b32_e64 v222, v79, 0, s[36:37]
	v_cndmask_b32_e64 v223, v80, 0, s[38:39]
	v_cndmask_b32_e64 v224, v81, 0, s[40:41]
	s_waitcnt lgkmcnt(0)
	v_mfma_f32_32x32x16_bf16 v[66:81], v[66:69], v[70:73], 0
	ds_read2_b64 v[216:219], v200 offset0:132 offset1:134
	v_cvt_pk_bf16_f32 v220, v169, v171
	v_cvt_pk_bf16_f32 v221, v189, v201
	v_cvt_pk_bf16_f32 v222, v202, v222
	v_cvt_pk_bf16_f32 v223, v223, v224
	v_lshlrev_b64 v[224:225], 1, v[84:85]
	v_add_u32_e32 v189, v140, v141
	v_lshl_add_u64 v[226:227], v[130:131], 0, v[224:225]
	s_waitcnt lgkmcnt(0)
	v_mfma_f32_32x32x16_bf16 v[66:81], v[220:223], v[216:219], v[66:81]
	ds_read2_b64 v[220:223], v189 offset1:2
	global_load_ushort v171, v[132:133], off
	global_load_ushort v217, v[232:233], off
	global_load_ushort v201, v[234:235], off
	global_load_ushort v169, v[236:237], off
	global_load_ushort v216, v[238:239], off
	global_load_ushort v202, v[226:227], off
	global_load_ushort v84, v224, s[60:61]
	global_load_ushort v218, v224, s[62:63]
	v_cvt_pk_bf16_f32 v224, v34, v35
	v_cvt_pk_bf16_f32 v225, v36, v37
	v_cvt_pk_bf16_f32 v226, v38, v39
	v_cvt_pk_bf16_f32 v227, v40, v41
	ds_read2_b64 v[228:231], v189 offset0:28 offset1:30
	v_mov_b32_e32 v132, s42
	s_waitcnt lgkmcnt(1)
	v_mfma_f32_32x32x16_bf16 v[66:81], v[220:223], v[224:227], v[66:81]
	ds_read2_b64 v[220:223], v189 offset0:4 offset1:6
	v_cvt_pk_bf16_f32 v224, v42, v43
	v_cvt_pk_bf16_f32 v225, v44, v45
	v_cvt_pk_bf16_f32 v226, v46, v47
	v_cvt_pk_bf16_f32 v227, v48, v49
	v_mov_b32_e32 v133, s59
	v_cndmask_b32_e64 v132, v132, v133, s[4:5]
	s_waitcnt lgkmcnt(0)
	v_mfma_f32_32x32x16_bf16 v[66:81], v[220:223], v[224:227], v[66:81]
	ds_read2_b64 v[220:223], v189 offset0:8 offset1:10
	v_cvt_pk_bf16_f32 v224, v50, v51
	v_cvt_pk_bf16_f32 v225, v52, v53
	v_cvt_pk_bf16_f32 v226, v54, v55
	v_cvt_pk_bf16_f32 v227, v56, v57
	s_waitcnt lgkmcnt(0)
	s_nop 0
	v_mfma_f32_32x32x16_bf16 v[66:81], v[220:223], v[224:227], v[66:81]
	ds_read2_b64 v[220:223], v189 offset0:12 offset1:14
	v_cvt_pk_bf16_f32 v224, v58, v59
	v_cvt_pk_bf16_f32 v225, v60, v61
	v_cvt_pk_bf16_f32 v226, v62, v63
	v_cvt_pk_bf16_f32 v227, v64, v65
	s_waitcnt lgkmcnt(0)
	s_nop 0
	v_mfma_f32_32x32x16_bf16 v[66:81], v[220:223], v[224:227], v[66:81]
	ds_read2_b64 v[220:223], v189 offset0:16 offset1:18
	v_cvt_pk_bf16_f32 v224, v18, v19
	v_cvt_pk_bf16_f32 v225, v20, v21
	v_cvt_pk_bf16_f32 v226, v22, v23
	v_cvt_pk_bf16_f32 v227, v24, v25
	s_waitcnt lgkmcnt(0)
	s_nop 0
	v_mfma_f32_32x32x16_bf16 v[66:81], v[220:223], v[224:227], v[66:81]
	ds_read2_b64 v[220:223], v189 offset0:20 offset1:22
	v_cvt_pk_bf16_f32 v224, v26, v27
	v_cvt_pk_bf16_f32 v225, v28, v29
	v_cvt_pk_bf16_f32 v226, v30, v31
	v_cvt_pk_bf16_f32 v227, v32, v33
	s_waitcnt lgkmcnt(0)
	s_nop 0
	v_mfma_f32_32x32x16_bf16 v[66:81], v[220:223], v[224:227], v[66:81]
	ds_read2_b64 v[220:223], v189 offset0:24 offset1:26
	v_cvt_pk_bf16_f32 v224, v2, v3
	v_cvt_pk_bf16_f32 v225, v4, v5
	v_cvt_pk_bf16_f32 v226, v6, v7
	v_cvt_pk_bf16_f32 v227, v8, v9
	s_waitcnt lgkmcnt(0)
	s_nop 0
	v_mfma_f32_32x32x16_bf16 v[66:81], v[220:223], v[224:227], v[66:81]
	v_cvt_pk_bf16_f32 v220, v10, v11
	v_cvt_pk_bf16_f32 v221, v12, v13
	v_cvt_pk_bf16_f32 v222, v14, v15
	v_cvt_pk_bf16_f32 v223, v16, v17
	s_nop 1
	v_mfma_f32_32x32x16_bf16 v[66:81], v[228:231], v[220:223], v[66:81]
	v_lshl_or_b32 v132, v132, 5, v143
	s_cmp_gt_u32 s59, 3
	v_mad_u64_u32 v[132:133], s[42:43], v132, s33, v[86:87]
	s_cselect_b64 s[74:75], -1, 0
	s_cmp_lt_u32 s59, 4
	s_cbranch_scc1 .LBB0_719
	ds_read_u16 v133, v132
	s_waitcnt lgkmcnt(0)
	v_lshlrev_b32_e32 v133, 16, v133
	s_nop 2
	v_add_f32_e32 v66, v66, v133

.LBB0_901:
	s_ashr_i32 s42, s95, 3
	s_add_i32 s42, s42, 32
	s_and_b32 s44, s95, 7
	s_lshl_b32 s56, s42, 8
	s_lshl_b32 s43, s44, 1
	s_lshl_b32 s42, s42, 4
	s_or_b32 s42, s42, s43
	s_addk_i32 s42, 0xfe00
	v_add_u32_e32 v2, s42, v85
	v_ashrrev_i32_e32 v3, 31, v2
	v_lshlrev_b64 v[2:3], 16, v[2:3]
	v_lshl_add_u64 v[46:47], v[88:89], 0, v[2:3]
	v_add_co_u32_e32 v2, vcc, s51, v46
	s_ashr_i32 s57, s56, 31
	s_nop 0
	v_addc_co_u32_e32 v3, vcc, 0, v47, vcc
	v_add_co_u32_e32 v66, vcc, s77, v46
	s_lshl_b32 s46, s44, 7
	s_nop 0
	v_addc_co_u32_e32 v67, vcc, 0, v47, vcc
	v_add_co_u32_e32 v8, vcc, s78, v46
	s_lshl_b64 s[42:43], s[56:57], 11
	s_nop 0
	v_addc_co_u32_e32 v9, vcc, 0, v47, vcc
	v_add_co_u32_e32 v6, vcc, s79, v46
	global_load_dword v50, v[46:47], off
	global_load_dword v51, v[46:47], off offset:512
	global_load_dword v52, v[46:47], off offset:1024
	global_load_dword v53, v[46:47], off offset:1536
	global_load_dword v55, v[2:3], off offset:512
	global_load_dword v56, v[2:3], off offset:1024
	global_load_dword v57, v[2:3], off offset:1536
	global_load_dword v63, v[8:9], off offset:512
	v_addc_co_u32_e32 v7, vcc, 0, v47, vcc
	v_add_co_u32_e32 v10, vcc, s80, v46
	s_add_u32 s45, s55, s42
	s_nop 0
	v_addc_co_u32_e32 v11, vcc, 0, v47, vcc
	v_add_co_u32_e32 v18, vcc, s81, v46
	s_addc_u32 s47, s74, s43
	s_nop 0
	v_addc_co_u32_e32 v19, vcc, 0, v47, vcc
	v_add_co_u32_e32 v12, vcc, s82, v46
	global_load_dword v60, v[66:67], off offset:1024
	global_load_dword v61, v[66:67], off offset:1536
	global_load_dword v62, v[6:7], off offset:-4096
	global_load_dword v2, v[6:7], off
	global_load_dword v3, v[6:7], off offset:512
	global_load_dword v4, v[6:7], off offset:1024
	global_load_dword v5, v[6:7], off offset:1536
	s_nop 0
	global_load_dword v6, v[18:19], off offset:-4096
	v_addc_co_u32_e32 v13, vcc, 0, v47, vcc
	v_add_co_u32_e32 v22, vcc, s83, v46
	s_lshl_b32 s52, s44, 8
	s_nop 0
	v_addc_co_u32_e32 v23, vcc, 0, v47, vcc
	v_add_co_u32_e32 v32, vcc, s84, v46
	global_load_dword v64, v[8:9], off offset:1024
	global_load_dword v65, v[8:9], off offset:1536
	global_load_dword v7, v[10:11], off offset:512
	s_nop 0
	global_load_dword v8, v[10:11], off offset:1024
	global_load_dword v9, v[10:11], off offset:1536
	global_load_dword v15, v[12:13], off offset:512
	global_load_dword v16, v[12:13], off offset:1024
	global_load_dword v17, v[12:13], off offset:1536
	s_nop 0
	global_load_dword v10, v[18:19], off
	global_load_dword v11, v[18:19], off offset:512
	global_load_dword v12, v[18:19], off offset:1024
	global_load_dword v13, v[18:19], off offset:1536
	global_load_dword v14, v[22:23], off offset:-4096
	s_nop 0
	global_load_dword v18, v[22:23], off
	global_load_dword v19, v[22:23], off offset:512
	global_load_dword v20, v[22:23], off offset:1024
	v_addc_co_u32_e32 v33, vcc, 0, v47, vcc
	v_add_co_u32_e32 v24, vcc, s85, v46
	s_add_u32 s58, s45, s52
	s_nop 0
	v_addc_co_u32_e32 v25, vcc, 0, v47, vcc
	v_add_co_u32_e32 v36, vcc, s86, v46
	s_addc_u32 s59, s47, 0
	s_nop 0
	v_addc_co_u32_e32 v37, vcc, 0, v47, vcc
	v_add_co_u32_e32 v42, vcc, s87, v46
	s_add_u32 s44, s75, s42
	s_nop 0
	v_addc_co_u32_e32 v43, vcc, 0, v47, vcc
	v_add_co_u32_e32 v48, vcc, s88, v46
	global_load_dword v21, v[22:23], off offset:1536
	s_nop 0
	global_load_dword v22, v[24:25], off offset:-4096
	global_load_dword v26, v[24:25], off
	global_load_dword v27, v[24:25], off offset:512
	global_load_dword v28, v[24:25], off offset:1024
	global_load_dword v29, v[24:25], off offset:1536
	global_load_dword v30, v[42:43], off offset:-4096
	global_load_dword v34, v[42:43], off
	v_addc_co_u32_e32 v49, vcc, 0, v47, vcc
	v_add_co_u32_e32 v58, vcc, s89, v46
	s_addc_u32 s45, s76, s43
	s_nop 0
	v_addc_co_u32_e32 v59, vcc, 0, v47, vcc
	global_load_dword v23, v[32:33], off offset:512
	global_load_dword v24, v[32:33], off offset:1024
	global_load_dword v25, v[32:33], off offset:1536
	global_load_dword v31, v[36:37], off offset:512
	s_nop 0
	global_load_dword v32, v[36:37], off offset:1024
	global_load_dword v33, v[36:37], off offset:1536
	global_load_dword v39, v[48:49], off offset:512
	global_load_dword v40, v[48:49], off offset:1024
	global_load_dword v35, v[42:43], off offset:512
	s_nop 0
	global_load_dword v36, v[42:43], off offset:1024
	global_load_dword v37, v[42:43], off offset:1536
	global_load_dword v38, v[58:59], off offset:-4096
	s_nop 0
	global_load_dword v42, v[58:59], off
	global_load_dword v43, v[58:59], off offset:512
	global_load_dword v44, v[58:59], off offset:1024
	global_load_dword v45, v[58:59], off offset:1536
	v_add_co_u32_e32 v58, vcc, s90, v46
	s_add_u32 s60, s44, s52
	s_nop 0
	v_addc_co_u32_e32 v59, vcc, 0, v47, vcc
	v_lshl_add_u64 v[46:47], v[86:87], 0, s[42:43]
	v_lshl_add_u64 v[126:127], v[46:47], 0, s[52:53]
	v_mov_b32_e32 v95, v83
	s_addc_u32 s61, s45, 0
	v_lshl_add_u64 v[68:69], v[126:127], 0, v[94:95]
	v_lshl_add_u64 v[70:71], v[126:127], 0, v[96:97]
	global_load_dword v41, v[48:49], off offset:1536
	global_load_dword v46, v[58:59], off
	global_load_dword v47, v[58:59], off offset:512
	s_nop 0
	global_load_dword v48, v[58:59], off offset:1024
	global_load_dword v49, v[58:59], off offset:1536
	global_load_ushort v179, v[68:69], off
	global_load_ushort v180, v[70:71], off
	global_load_ushort v175, v96, s[58:59]
	v_lshl_add_u64 v[68:69], v[126:127], 0, v[98:99]
	v_lshl_add_u64 v[74:75], v[126:127], 0, v[100:101]
	v_lshl_add_u64 v[80:81], v[126:127], 0, v[102:103]
	global_load_ushort v187, v96, s[60:61]
	global_load_ushort v181, v[68:69], off
	global_load_ushort v169, v98, s[58:59]
	global_load_ushort v188, v98, s[60:61]
	global_load_ushort v184, v[74:75], off
	global_load_ushort v171, v100, s[58:59]
	global_load_ushort v206, v100, s[60:61]
	global_load_ushort v183, v[80:81], off
	v_lshl_add_u64 v[70:71], v[126:127], 0, v[104:105]
	v_lshl_add_u64 v[76:77], v[126:127], 0, v[106:107]
	global_load_ushort v167, v102, s[58:59]
	global_load_ushort v207, v102, s[60:61]
	global_load_ushort v185, v[70:71], off
	global_load_ushort v178, v104, s[58:59]
	global_load_ushort v208, v104, s[60:61]
	global_load_ushort v186, v[76:77], off
	global_load_ushort v177, v106, s[58:59]
	global_load_ushort v209, v106, s[60:61]
	v_lshl_add_u64 v[58:59], v[126:127], 0, v[108:109]
	v_lshl_add_u64 v[72:73], v[126:127], 0, v[110:111]
	v_lshl_add_u64 v[78:79], v[126:127], 0, v[112:113]
	global_load_ushort v189, v[58:59], off
	global_load_ushort v176, v108, s[58:59]
	global_load_ushort v210, v108, s[60:61]
	global_load_ushort v190, v[72:73], off
	global_load_ushort v172, v110, s[58:59]
	global_load_ushort v211, v110, s[60:61]
	global_load_ushort v191, v[78:79], off
	global_load_ushort v168, v112, s[58:59]
	v_lshl_add_u64 v[194:195], v[126:127], 0, v[120:121]
	v_lshl_add_u64 v[200:201], v[126:127], 0, v[122:123]
	global_load_ushort v95, v118, s[58:59]
	global_load_ushort v212, v118, s[60:61]
	s_nop 0
	global_load_ushort v192, v[194:195], off
	global_load_ushort v170, v120, s[58:59]
	s_nop 0
	global_load_ushort v199, v120, s[60:61]
	s_nop 0
	global_load_ushort v197, v[200:201], off
	global_load_ushort v166, v122, s[58:59]
	s_nop 0
	global_load_ushort v204, v122, s[60:61]
	v_lshl_add_u64 v[194:195], v[126:127], 0, v[124:125]
	v_lshl_add_u64 v[70:71], v[126:127], 0, v[114:115]
	v_lshl_add_u64 v[76:77], v[126:127], 0, v[116:117]
	v_lshl_add_u64 v[78:79], s[58:59], 0, v[116:117]
	v_lshl_add_u64 v[80:81], s[60:61], 0, v[116:117]
	v_lshl_add_u64 v[128:129], v[126:127], 0, v[118:119]
	v_lshl_add_u64 v[202:203], s[60:61], 0, v[124:125]
	global_load_dword v54, v[66:67], off offset:-4096
	global_load_dword v58, v[66:67], off
	global_load_dword v59, v[66:67], off offset:512
	global_load_ushort v182, v94, s[58:59]
	s_nop 0
	global_load_ushort v66, v94, s[60:61]
	global_load_ushort v198, v[194:195], off
	global_load_ushort v82, v124, s[58:59]
	s_nop 0
	global_load_ushort v195, v[202:203], off
	global_load_ushort v200, v112, s[60:61]
	s_nop 0
	global_load_ushort v74, v114, s[60:61]
	s_nop 0
	global_load_ushort v75, v[80:81], off
	global_load_ushort v193, v[70:71], off
	global_load_ushort v173, v114, s[58:59]
	global_load_ushort v196, v[76:77], off
	global_load_ushort v174, v[78:79], off
	global_load_ushort v194, v[128:129], off
	s_mov_b32 s47, 6
	s_mov_b32 s45, 0
	s_waitcnt vmcnt(0)
	v_lshl_or_b32 v67, v206, 16, v188
	v_lshl_or_b32 v68, v208, 16, v207
	v_lshl_or_b32 v69, v210, 16, v209
	v_lshl_or_b32 v72, v199, 16, v212
	v_lshl_or_b32 v66, v187, 16, v66
	v_lshl_or_b32 v73, v195, 16, v204
	v_lshl_or_b32 v70, v200, 16, v211
	v_lshl_or_b32 v71, v75, 16, v74
.LBB0_902:
	v_cvt_f32_f16_e32 v75, v179
	v_cvt_f32_f16_e32 v77, v180
	v_cvt_f32_f16_e32 v80, v181
	v_cvt_f32_f16_e32 v81, v184
	v_add_f32_e32 v74, 0, v75
	v_cvt_f32_f16_e32 v179, v183
	v_add_f32_e32 v79, v74, v77
	v_cvt_f32_f16_e32 v180, v185
	v_add_f32_e32 v128, v79, v80
	v_cvt_f32_f16_e32 v181, v186
	v_add_f32_e32 v129, v128, v81
	v_cvt_f32_f16_e32 v183, v189
	v_add_f32_e32 v184, v129, v179
	v_cvt_f32_f16_e32 v188, v190
	v_add_f32_e32 v185, v184, v180
	v_cvt_f32_f16_e32 v189, v191
	v_add_f32_e32 v186, v185, v181
	v_cvt_f32_f16_e32 v190, v193
	v_add_f32_e32 v187, v186, v183
	v_cvt_f32_f16_e32 v191, v196
	v_add_f32_e32 v193, v187, v188
	v_cvt_f32_f16_e32 v194, v194
	v_add_f32_e32 v195, v193, v189
	v_cvt_f32_f16_e32 v192, v192
	v_add_f32_e32 v196, v195, v190
	v_cvt_f32_f16_e32 v197, v197
	v_add_f32_e32 v199, v196, v191
	v_cvt_f32_f16_e32 v198, v198
	v_add_f32_e32 v200, v199, v194
	v_add_f32_e32 v201, v200, v192
	v_add_f32_e32 v202, v201, v197
	v_add_f32_e32 v203, v202, v198
	ds_bpermute_b32 v76, v154, v203
	v_mul_f32_e32 v75, 0x3fb8aa3b, v75
	v_lshlrev_b32_e32 v95, 16, v95
	s_waitcnt lgkmcnt(0)
	v_cndmask_b32_e64 v204, v76, 0, s[6:7]
	v_add_f32_e32 v74, v74, v204
	v_mul_f32_e32 v74, 0x3fb8aa3b, v74
	v_exp_f32_e32 v205, v74
	v_add_f32_e32 v79, v79, v204
	v_add_f32_e32 v78, v203, v76
	v_exp_f32_e32 v76, v75
	v_lshlrev_b32_e32 v75, 16, v182
	v_mul_f32_e32 v79, 0x3fb8aa3b, v79
	v_mul_f32_e32 v75, v205, v75
	v_exp_f32_e32 v182, v79
	v_cvt_pk_bf16_f32 v75, v75, s0
	ds_write_b16 v163, v75
	v_mul_f32_e32 v75, 0x3fb8aa3b, v77
	v_mul_f32_e32 v78, 0x3fb8aa3b, v78
	v_exp_f32_e32 v77, v75
	v_exp_f32_e32 v74, v78
	v_rcp_f32_e32 v78, v205
	v_rcp_f32_e32 v79, v182
	v_lshlrev_b32_e32 v75, 16, v175
	v_mul_f32_e32 v75, v182, v75
	v_pk_add_f32 v[76:77], v[76:77], 1.0 op_sel_hi:[1,0] neg_lo:[1,0] neg_hi:[1,0]
	v_cvt_pk_bf16_f32 v75, v75, s0
	v_pk_mul_f32 v[76:77], v[76:77], v[78:79]
	ds_write_b16 v163, v75 offset:272
	v_cvt_pk_bf16_f32 v75, v76, s0
	ds_write_b16 v163, v75 offset:8704
	v_cvt_pk_bf16_f32 v75, v77, s0
	ds_write_b16 v163, v75 offset:8976
	v_add_f32_e32 v75, v128, v204
	v_mul_f32_e32 v75, 0x3fb8aa3b, v75
	v_exp_f32_e32 v75, v75
	v_lshlrev_b32_e32 v79, 16, v169
	v_mul_f32_e32 v78, 0x3fb8aa3b, v80
	v_exp_f32_e32 v78, v78
	v_pk_mul_f32 v[76:77], v[74:75], v[76:77] op_sel_hi:[0,1]
	v_rcp_f32_e32 v80, v75
	v_mul_f32_e32 v75, v75, v79
	v_add_f32_e32 v79, v129, v204
	v_mul_f32_e32 v79, 0x3fb8aa3b, v79
	v_exp_f32_e32 v128, v79
	v_cvt_pk_bf16_f32 v75, v75, s0
	ds_write_b16 v163, v75 offset:544
	v_mul_f32_e32 v75, 0x3fb8aa3b, v81
	v_exp_f32_e32 v79, v75
	v_rcp_f32_e32 v81, v128
	v_lshlrev_b32_e32 v75, 16, v171
	v_mul_f32_e32 v75, v128, v75
	v_pk_add_f32 v[78:79], v[78:79], 1.0 op_sel_hi:[1,0] neg_lo:[1,0] neg_hi:[1,0]
	v_cvt_pk_bf16_f32 v75, v75, s0
	v_pk_mul_f32 v[78:79], v[78:79], v[80:81]
	ds_write_b16 v163, v75 offset:816
	v_cvt_pk_bf16_f32 v75, v78, s0
	ds_write_b16 v163, v75 offset:9248
	v_cvt_pk_bf16_f32 v75, v79, s0
	ds_write_b16 v163, v75 offset:9520
	v_add_f32_e32 v75, v184, v204
	v_mul_f32_e32 v75, 0x3fb8aa3b, v75
	v_exp_f32_e32 v75, v75
	v_lshlrev_b32_e32 v81, 16, v167
	v_mul_f32_e32 v80, 0x3fb8aa3b, v179
	v_exp_f32_e32 v80, v80
	v_pk_mul_f32 v[78:79], v[74:75], v[78:79] op_sel_hi:[0,1]
	v_rcp_f32_e32 v128, v75
	v_mul_f32_e32 v75, v75, v81
	v_add_f32_e32 v81, v185, v204
	v_mul_f32_e32 v81, 0x3fb8aa3b, v81
	v_exp_f32_e32 v167, v81
	v_cvt_pk_bf16_f32 v75, v75, s0
	ds_write_b16 v163, v75 offset:1088
	v_mul_f32_e32 v75, 0x3fb8aa3b, v180
	v_exp_f32_e32 v81, v75
	v_rcp_f32_e32 v129, v167
	v_lshlrev_b32_e32 v75, 16, v178
	v_mul_f32_e32 v75, v167, v75
	v_pk_add_f32 v[80:81], v[80:81], 1.0 op_sel_hi:[1,0] neg_lo:[1,0] neg_hi:[1,0]
	v_cvt_pk_bf16_f32 v75, v75, s0
	v_pk_mul_f32 v[80:81], v[80:81], v[128:129]
	ds_write_b16 v163, v75 offset:1360
	v_cvt_pk_bf16_f32 v75, v80, s0
	ds_write_b16 v163, v75 offset:9792
	v_cvt_pk_bf16_f32 v75, v81, s0
	ds_write_b16 v163, v75 offset:10064
	v_add_f32_e32 v75, v186, v204
	v_mul_f32_e32 v75, 0x3fb8aa3b, v75
	v_exp_f32_e32 v75, v75
	v_lshlrev_b32_e32 v129, 16, v177
	v_mul_f32_e32 v128, 0x3fb8aa3b, v181
	v_exp_f32_e32 v128, v128
	v_pk_mul_f32 v[80:81], v[74:75], v[80:81] op_sel_hi:[0,1]
	v_rcp_f32_e32 v178, v75
	v_mul_f32_e32 v75, v75, v129
	v_add_f32_e32 v129, v187, v204
	v_mul_f32_e32 v129, 0x3fb8aa3b, v129
	v_exp_f32_e32 v167, v129
	v_cvt_pk_bf16_f32 v75, v75, s0
	ds_write_b16 v163, v75 offset:1632
	v_mul_f32_e32 v75, 0x3fb8aa3b, v183
	v_exp_f32_e32 v129, v75
	v_rcp_f32_e32 v179, v167
	v_lshlrev_b32_e32 v75, 16, v176
	v_mul_f32_e32 v75, v167, v75
	v_pk_add_f32 v[128:129], v[128:129], 1.0 op_sel_hi:[1,0] neg_lo:[1,0] neg_hi:[1,0]
	v_cvt_pk_bf16_f32 v75, v75, s0
	v_pk_mul_f32 v[128:129], v[128:129], v[178:179]
	ds_write_b16 v163, v75 offset:1904
	v_cvt_pk_bf16_f32 v75, v128, s0
	ds_write_b16 v163, v75 offset:10336
	v_cvt_pk_bf16_f32 v75, v129, s0
	ds_write_b16 v163, v75 offset:10608
	v_add_f32_e32 v75, v193, v204
	v_mul_f32_e32 v75, 0x3fb8aa3b, v75
	v_exp_f32_e32 v75, v75
	v_mul_f32_e32 v167, 0x3fb8aa3b, v188
	v_exp_f32_e32 v176, v167
	v_lshlrev_b32_e32 v167, 16, v172
	v_pk_mul_f32 v[128:129], v[74:75], v[128:129] op_sel_hi:[0,1]
	v_rcp_f32_e32 v178, v75
	v_mul_f32_e32 v75, v75, v167
	v_add_f32_e32 v167, v195, v204
	v_mul_f32_e32 v167, 0x3fb8aa3b, v167
	v_exp_f32_e32 v167, v167
	v_cvt_pk_bf16_f32 v75, v75, s0
	ds_write_b16 v163, v75 offset:2176
	v_mul_f32_e32 v75, 0x3fb8aa3b, v189
	v_exp_f32_e32 v177, v75
	v_rcp_f32_e32 v179, v167
	v_lshlrev_b32_e32 v75, 16, v168
	v_mul_f32_e32 v75, v167, v75
	v_pk_add_f32 v[168:169], v[176:177], 1.0 op_sel_hi:[1,0] neg_lo:[1,0] neg_hi:[1,0]
	v_cvt_pk_bf16_f32 v75, v75, s0
	v_pk_mul_f32 v[168:169], v[168:169], v[178:179]
	ds_write_b16 v163, v75 offset:2448
	v_cvt_pk_bf16_f32 v75, v168, s0
	ds_write_b16 v163, v75 offset:10880
	v_cvt_pk_bf16_f32 v75, v169, s0
	ds_write_b16 v163, v75 offset:11152
	v_add_f32_e32 v75, v196, v204
	v_mul_f32_e32 v75, 0x3fb8aa3b, v75
	v_exp_f32_e32 v75, v75
	v_mul_f32_e32 v167, 0x3fb8aa3b, v190
	v_exp_f32_e32 v172, v167
	v_lshlrev_b32_e32 v167, 16, v173
	v_pk_mul_f32 v[168:169], v[74:75], v[168:169] op_sel_hi:[0,1]
	v_rcp_f32_e32 v176, v75
	v_mul_f32_e32 v75, v75, v167
	v_add_f32_e32 v167, v199, v204
	v_mul_f32_e32 v167, 0x3fb8aa3b, v167
	v_exp_f32_e32 v167, v167
	v_cvt_pk_bf16_f32 v75, v75, s0
	ds_write_b16 v163, v75 offset:2720
	v_mul_f32_e32 v75, 0x3fb8aa3b, v191
	v_exp_f32_e32 v173, v75
	v_rcp_f32_e32 v177, v167
	v_lshlrev_b32_e32 v75, 16, v174
	v_mul_f32_e32 v75, v167, v75
	v_pk_add_f32 v[172:173], v[172:173], 1.0 op_sel_hi:[1,0] neg_lo:[1,0] neg_hi:[1,0]
	v_cvt_pk_bf16_f32 v75, v75, s0
	v_pk_mul_f32 v[172:173], v[172:173], v[176:177]
	ds_write_b16 v163, v75 offset:2992
	v_cvt_pk_bf16_f32 v75, v172, s0
	ds_write_b16 v163, v75 offset:11424
	v_cvt_pk_bf16_f32 v75, v173, s0
	ds_write_b16 v163, v75 offset:11696
	v_add_f32_e32 v75, v200, v204
	v_mul_f32_e32 v75, 0x3fb8aa3b, v75
	v_exp_f32_e32 v75, v75
	v_mul_f32_e32 v167, 0x3fb8aa3b, v194
	v_exp_f32_e32 v174, v167
	v_cvt_pk_bf16_f32 v76, v76, v77
	v_pk_mul_f32 v[172:173], v[74:75], v[172:173] op_sel_hi:[0,1]
	v_rcp_f32_e32 v176, v75
	v_mul_f32_e32 v75, v75, v95
	v_add_f32_e32 v95, v201, v204
	v_mul_f32_e32 v95, 0x3fb8aa3b, v95
	v_exp_f32_e32 v95, v95
	v_cvt_pk_bf16_f32 v75, v75, s0
	ds_write_b16 v163, v75 offset:3264
	v_mul_f32_e32 v75, 0x3fb8aa3b, v192
	v_exp_f32_e32 v175, v75
	v_rcp_f32_e32 v177, v95
	v_lshlrev_b32_e32 v75, 16, v170
	v_mul_f32_e32 v75, v95, v75
	v_pk_add_f32 v[170:171], v[174:175], 1.0 op_sel_hi:[1,0] neg_lo:[1,0] neg_hi:[1,0]
	v_cvt_pk_bf16_f32 v75, v75, s0
	v_pk_mul_f32 v[170:171], v[170:171], v[176:177]
	ds_write_b16 v163, v75 offset:3536
	v_cvt_pk_bf16_f32 v75, v170, s0
	ds_write_b16 v163, v75 offset:11968
	v_cvt_pk_bf16_f32 v75, v171, s0
	ds_write_b16 v163, v75 offset:12240
	v_add_f32_e32 v75, v202, v204
	v_mul_f32_e32 v75, 0x3fb8aa3b, v75
	v_exp_f32_e32 v75, v75
	v_mul_f32_e32 v95, 0x3fb8aa3b, v197
	v_exp_f32_e32 v174, v95
	v_lshlrev_b32_e32 v95, 16, v166
	v_pk_mul_f32 v[170:171], v[74:75], v[170:171] op_sel_hi:[0,1]
	v_rcp_f32_e32 v176, v75
	v_mul_f32_e32 v75, v75, v95
	v_add_f32_e32 v95, v203, v204
	v_mul_f32_e32 v95, 0x3fb8aa3b, v95
	v_exp_f32_e32 v95, v95
	v_cvt_pk_bf16_f32 v75, v75, s0
	ds_write_b16 v163, v75 offset:3808
	v_mul_f32_e32 v75, 0x3fb8aa3b, v198
	v_exp_f32_e32 v175, v75
	v_rcp_f32_e32 v177, v95
	v_lshlrev_b32_e32 v75, 16, v82
	v_mul_f32_e32 v75, v95, v75
	v_pk_add_f32 v[166:167], v[174:175], 1.0 op_sel_hi:[1,0] neg_lo:[1,0] neg_hi:[1,0]
	v_cvt_pk_bf16_f32 v75, v75, s0
	v_pk_mul_f32 v[166:167], v[166:167], v[176:177]
	ds_write_b16 v163, v75 offset:4080
	v_cvt_pk_bf16_f32 v75, v166, s0
	ds_write_b16 v163, v75 offset:12512
	v_cvt_pk_bf16_f32 v75, v167, s0
	v_pk_mul_f32 v[174:175], v[74:75], v[166:167] op_sel_hi:[0,1]
	v_cvt_pk_bf16_f32 v77, v78, v79
	v_cvt_pk_bf16_f32 v78, v80, v81
	v_cvt_pk_bf16_f32 v79, v128, v129
	ds_write_b16 v163, v75 offset:12784
	v_cvt_pk_bf16_f32 v166, v168, v169
	v_cvt_pk_bf16_f32 v167, v172, v173
	v_cvt_pk_bf16_f32 v168, v170, v171
	v_cvt_pk_bf16_f32 v169, v174, v175
	ds_write_b128 v164, v[76:79] offset:17408
	ds_write_b128 v164, v[166:169] offset:17424
	ds_write_b128 v164, v[66:69] offset:27648
	ds_write_b128 v164, v[70:73] offset:27664
	s_and_saveexec_b64 s[42:43], s[6:7]
	v_add_u32_e32 v66, v132, v134
	ds_write_b32 v66, v74 offset:37888
	s_or_b64 exec, exec, s[42:43]
	s_add_i32 s44, s45, 1
	v_mov_b32_e32 v66, s47
	v_mov_b32_e32 v67, s44
	v_cndmask_b32_e64 v66, v66, v67, s[4:5]
	v_lshl_or_b32 v82, v66, 15, v160
	v_lshlrev_b64 v[66:67], 1, v[82:83]
	v_add_u32_e32 v82, v82, v130
	v_lshlrev_b64 v[72:73], 1, v[82:83]
	v_add_u32_e32 v82, v82, v130
	v_lshl_add_u64 v[68:69], v[126:127], 0, v[66:67]
	v_lshlrev_b64 v[78:79], 1, v[82:83]
	v_add_u32_e32 v82, v82, v130
	s_waitcnt lgkmcnt(0)
	s_barrier
	v_lshl_add_u64 v[74:75], v[126:127], 0, v[72:73]
	v_lshl_add_u64 v[80:81], v[126:127], 0, v[78:79]
	global_load_ushort v179, v[68:69], off
	global_load_ushort v182, v66, s[58:59]
	global_load_ushort v199, v66, s[60:61]
	global_load_ushort v180, v[74:75], off
	global_load_ushort v175, v72, s[58:59]
	global_load_ushort v200, v72, s[60:61]
	global_load_ushort v181, v[80:81], off
	global_load_ushort v169, v78, s[58:59]
	v_lshlrev_b64 v[68:69], 1, v[82:83]
	v_add_u32_e32 v82, v82, v130
	v_lshlrev_b64 v[74:75], 1, v[82:83]
	v_add_u32_e32 v82, v82, v130
	v_lshlrev_b64 v[80:81], 1, v[82:83]
	v_add_u32_e32 v82, v82, v130
	v_lshl_add_u64 v[70:71], v[126:127], 0, v[68:69]
	v_lshl_add_u64 v[76:77], v[126:127], 0, v[74:75]
	v_lshl_add_u64 v[128:129], v[126:127], 0, v[80:81]
	global_load_ushort v201, v78, s[60:61]
	global_load_ushort v184, v[70:71], off
	global_load_ushort v171, v68, s[58:59]
	global_load_ushort v203, v68, s[60:61]
	global_load_ushort v183, v[76:77], off
	global_load_ushort v167, v74, s[58:59]
	global_load_ushort v202, v74, s[60:61]
	global_load_ushort v185, v[128:129], off
	v_lshlrev_b64 v[66:67], 1, v[82:83]
	v_add_u32_e32 v82, v82, v130
	v_lshl_add_u64 v[74:75], v[126:127], 0, v[66:67]
	v_lshl_add_u64 v[76:77], s[58:59], 0, v[66:67]
	v_lshl_add_u64 v[78:79], s[60:61], 0, v[66:67]
	v_lshlrev_b64 v[66:67], 1, v[82:83]
	v_add_u32_e32 v188, v135, v131
	v_lshl_add_u64 v[70:71], s[58:59], 0, v[80:81]
	v_lshl_add_u64 v[72:73], s[60:61], 0, v[80:81]
	v_lshl_add_u64 v[80:81], v[126:127], 0, v[66:67]
	v_lshl_add_u64 v[128:129], s[58:59], 0, v[66:67]
	v_lshl_add_u64 v[172:173], s[60:61], 0, v[66:67]
	ds_read_b128 v[66:69], v188 offset:8704
	global_load_ushort v178, v[70:71], off
	global_load_ushort v205, v[72:73], off
	global_load_ushort v186, v[74:75], off
	global_load_ushort v177, v[76:77], off
	global_load_ushort v204, v[78:79], off
	global_load_ushort v189, v[80:81], off
	global_load_ushort v176, v[128:129], off
	global_load_ushort v206, v[172:173], off
	ds_read_b128 v[70:73], v165
	s_waitcnt lgkmcnt(0)
	v_mfma_f32_32x32x16_bf16 v[66:81], v[66:69], v[70:73], 0
	ds_read_b128 v[190:193], v188 offset:8736
	ds_read_b128 v[194:197], v165 offset:32
	v_add_u32_e32 v82, v82, v130
	v_lshlrev_b64 v[128:129], 1, v[82:83]
	v_add_u32_e32 v82, v82, v130
	v_lshlrev_b64 v[208:209], 1, v[82:83]
	v_lshl_add_u64 v[218:219], v[126:127], 0, v[208:209]
	v_lshl_add_u64 v[220:221], s[58:59], 0, v[208:209]
	v_lshl_add_u64 v[222:223], s[60:61], 0, v[208:209]
	ds_read_b128 v[208:211], v188 offset:8768
	s_waitcnt lgkmcnt(1)
	v_mfma_f32_32x32x16_bf16 v[66:81], v[190:193], v[194:197], v[66:81]
	ds_read_b128 v[190:193], v165 offset:64
	ds_read_b128 v[194:197], v188 offset:8800
	ds_read_b128 v[212:215], v165 offset:96
	v_add_u32_e32 v82, v82, v130
	v_lshl_add_u64 v[172:173], v[126:127], 0, v[128:129]
	v_lshlrev_b64 v[224:225], 1, v[82:83]
	s_waitcnt lgkmcnt(2)
	v_mfma_f32_32x32x16_bf16 v[66:81], v[208:211], v[190:193], v[66:81]
	v_lshl_add_u64 v[226:227], v[126:127], 0, v[224:225]
	global_load_ushort v190, v[172:173], off
	s_nop 0
	global_load_ushort v172, v128, s[58:59]
	global_load_ushort v207, v128, s[60:61]
	global_load_ushort v191, v[218:219], off
	global_load_ushort v168, v[220:221], off
	global_load_ushort v208, v[222:223], off
	global_load_ushort v193, v[226:227], off
	global_load_ushort v173, v224, s[58:59]
	ds_read_b128 v[216:219], v188 offset:8832
	v_add_u32_e32 v82, v82, v130
	v_lshlrev_b64 v[210:211], 1, v[82:83]
	v_lshl_add_u64 v[128:129], s[60:61], 0, v[224:225]
	s_waitcnt lgkmcnt(1)
	v_mfma_f32_32x32x16_bf16 v[66:81], v[194:197], v[212:215], v[66:81]
	ds_read_b128 v[194:197], v165 offset:128
	v_lshl_add_u64 v[224:225], v[126:127], 0, v[210:211]
	v_lshl_add_u64 v[226:227], s[58:59], 0, v[210:211]
	v_lshl_add_u64 v[228:229], s[60:61], 0, v[210:211]
	ds_read_b128 v[210:213], v188 offset:8864
	ds_read_b128 v[220:223], v165 offset:160
	v_add_u32_e32 v82, v82, v130
	s_add_i32 s42, s47, 1
	s_waitcnt lgkmcnt(2)
	v_mfma_f32_32x32x16_bf16 v[66:81], v[216:219], v[194:197], v[66:81]
	v_lshlrev_b64 v[194:195], 1, v[82:83]
	v_add_u32_e32 v82, v82, v130
	v_lshlrev_b64 v[236:237], 1, v[82:83]
	v_lshl_add_u64 v[230:231], v[126:127], 0, v[194:195]
	v_lshl_add_u64 v[232:233], s[58:59], 0, v[194:195]
	v_lshl_add_u64 v[234:235], s[60:61], 0, v[194:195]
	v_lshl_add_u64 v[238:239], v[126:127], 0, v[236:237]
	s_waitcnt lgkmcnt(0)
	v_mfma_f32_32x32x16_bf16 v[66:81], v[210:213], v[220:223], v[66:81]
	ds_read_b128 v[212:215], v188 offset:8896
	ds_read_b128 v[216:219], v165 offset:192
	global_load_ushort v209, v[128:129], off
	global_load_ushort v196, v[224:225], off
	global_load_ushort v174, v[226:227], off
	global_load_ushort v211, v[228:229], off
	global_load_ushort v194, v[230:231], off
	global_load_ushort v95, v[232:233], off
	global_load_ushort v210, v[234:235], off
	global_load_ushort v192, v[238:239], off
	ds_read_b128 v[220:223], v188 offset:8928
	ds_read_b128 v[224:227], v165 offset:224
	v_add_u32_e32 v82, v82, v130
	v_lshl_add_u64 v[228:229], s[60:61], 0, v[236:237]
	s_waitcnt lgkmcnt(2)
	v_mfma_f32_32x32x16_bf16 v[66:81], v[212:215], v[216:219], v[66:81]
	v_lshlrev_b64 v[212:213], 1, v[82:83]
	v_lshl_add_u64 v[230:231], v[126:127], 0, v[212:213]
	v_lshl_add_u64 v[232:233], s[58:59], 0, v[212:213]
	v_lshl_add_u64 v[234:235], s[60:61], 0, v[212:213]
	v_add_u32_e32 v82, v82, v130
	s_waitcnt lgkmcnt(0)
	v_mfma_f32_32x32x16_bf16 v[66:81], v[220:223], v[224:227], v[66:81]
	s_nop 11
	v_cndmask_b32_e64 v166, v66, 0, s[8:9]
	v_cndmask_b32_e64 v66, v166, v66, s[10:11]
	v_cndmask_b32_e64 v67, 0, v67, s[10:11]
	v_cndmask_b32_e64 v68, v68, 0, s[12:13]
	v_cndmask_b32_e64 v69, v69, 0, s[14:15]
	v_cndmask_b32_e64 v70, v70, 0, s[16:17]
	v_cndmask_b32_e64 v71, v71, 0, s[18:19]
	v_cvt_pk_bf16_f32 v66, v66, v67
	v_cvt_pk_bf16_f32 v67, v68, v69
	v_cvt_pk_bf16_f32 v68, v70, v71
	v_add_u32_e32 v70, v132, v136
	v_cndmask_b32_e64 v72, v72, 0, s[20:21]
	v_cndmask_b32_e64 v73, v73, 0, s[22:23]
	v_add_u32_e32 v195, 0x6800, v70
	v_cvt_pk_bf16_f32 v69, v72, v73
	ds_read2_b64 v[70:73], v195 offset0:128 offset1:130
	v_cndmask_b32_e64 v166, v74, 0, s[24:25]
	v_cndmask_b32_e64 v170, v75, 0, s[26:27]
	v_cndmask_b32_e64 v187, v76, 0, s[28:29]
	v_cndmask_b32_e64 v197, v77, 0, s[30:31]
	v_cndmask_b32_e64 v198, v78, 0, s[34:35]
	v_cndmask_b32_e64 v218, v79, 0, s[36:37]
	v_cndmask_b32_e64 v219, v80, 0, s[38:39]
	v_cndmask_b32_e64 v220, v81, 0, s[40:41]
	s_waitcnt lgkmcnt(0)
	v_mfma_f32_32x32x16_bf16 v[66:81], v[66:69], v[70:73], 0
	ds_read2_b64 v[212:215], v195 offset0:132 offset1:134
	v_cvt_pk_bf16_f32 v216, v166, v170
	v_cvt_pk_bf16_f32 v217, v187, v197
	v_cvt_pk_bf16_f32 v218, v198, v218
	v_cvt_pk_bf16_f32 v219, v219, v220
	v_lshlrev_b64 v[220:221], 1, v[82:83]
	v_add_u32_e32 v187, v135, v136
	v_lshl_add_u64 v[222:223], v[126:127], 0, v[220:221]
	s_waitcnt lgkmcnt(0)
	v_mfma_f32_32x32x16_bf16 v[66:81], v[216:219], v[212:215], v[66:81]
	ds_read2_b64 v[216:219], v187 offset1:2
	global_load_ushort v170, v236, s[58:59]
	global_load_ushort v213, v[228:229], off
	global_load_ushort v197, v[230:231], off
	global_load_ushort v166, v[232:233], off
	global_load_ushort v212, v[234:235], off
	global_load_ushort v198, v[222:223], off
	global_load_ushort v82, v220, s[58:59]
	global_load_ushort v214, v220, s[60:61]
	v_cvt_pk_bf16_f32 v220, v50, v51
	v_cvt_pk_bf16_f32 v221, v52, v53
	v_cvt_pk_bf16_f32 v222, v54, v55
	v_cvt_pk_bf16_f32 v223, v56, v57
	ds_read2_b64 v[224:227], v187 offset0:28 offset1:30
	v_mov_b32_e32 v128, s42
	s_waitcnt lgkmcnt(1)
	v_mfma_f32_32x32x16_bf16 v[66:81], v[216:219], v[220:223], v[66:81]
	ds_read2_b64 v[216:219], v187 offset0:4 offset1:6
	v_cvt_pk_bf16_f32 v220, v58, v59
	v_cvt_pk_bf16_f32 v221, v60, v61
	v_cvt_pk_bf16_f32 v222, v62, v63
	v_cvt_pk_bf16_f32 v223, v64, v65
	v_mov_b32_e32 v129, s45
	v_cndmask_b32_e64 v128, v128, v129, s[4:5]
	s_waitcnt lgkmcnt(0)
	v_mfma_f32_32x32x16_bf16 v[66:81], v[216:219], v[220:223], v[66:81]
	ds_read2_b64 v[216:219], v187 offset0:8 offset1:10
	v_cvt_pk_bf16_f32 v220, v2, v3
	v_cvt_pk_bf16_f32 v221, v4, v5
	v_cvt_pk_bf16_f32 v222, v6, v7
	v_cvt_pk_bf16_f32 v223, v8, v9
	s_waitcnt lgkmcnt(0)
	s_nop 0
	v_mfma_f32_32x32x16_bf16 v[66:81], v[216:219], v[220:223], v[66:81]
	ds_read2_b64 v[216:219], v187 offset0:12 offset1:14
	v_cvt_pk_bf16_f32 v220, v10, v11
	v_cvt_pk_bf16_f32 v221, v12, v13
	v_cvt_pk_bf16_f32 v222, v14, v15
	v_cvt_pk_bf16_f32 v223, v16, v17
	s_waitcnt lgkmcnt(0)
	s_nop 0
	v_mfma_f32_32x32x16_bf16 v[66:81], v[216:219], v[220:223], v[66:81]
	ds_read2_b64 v[216:219], v187 offset0:16 offset1:18
	v_cvt_pk_bf16_f32 v220, v18, v19
	v_cvt_pk_bf16_f32 v221, v20, v21
	v_cvt_pk_bf16_f32 v222, v22, v23
	v_cvt_pk_bf16_f32 v223, v24, v25
	s_waitcnt lgkmcnt(0)
	s_nop 0
	v_mfma_f32_32x32x16_bf16 v[66:81], v[216:219], v[220:223], v[66:81]
	ds_read2_b64 v[216:219], v187 offset0:20 offset1:22
	v_cvt_pk_bf16_f32 v220, v26, v27
	v_cvt_pk_bf16_f32 v221, v28, v29
	v_cvt_pk_bf16_f32 v222, v30, v31
	v_cvt_pk_bf16_f32 v223, v32, v33
	s_waitcnt lgkmcnt(0)
	s_nop 0
	v_mfma_f32_32x32x16_bf16 v[66:81], v[216:219], v[220:223], v[66:81]
	ds_read2_b64 v[216:219], v187 offset0:24 offset1:26
	v_cvt_pk_bf16_f32 v220, v34, v35
	v_cvt_pk_bf16_f32 v221, v36, v37
	v_cvt_pk_bf16_f32 v222, v38, v39
	v_cvt_pk_bf16_f32 v223, v40, v41
	s_waitcnt lgkmcnt(0)
	s_nop 0
	v_mfma_f32_32x32x16_bf16 v[66:81], v[216:219], v[220:223], v[66:81]
	v_cvt_pk_bf16_f32 v216, v42, v43
	v_cvt_pk_bf16_f32 v217, v44, v45
	v_cvt_pk_bf16_f32 v218, v46, v47
	v_cvt_pk_bf16_f32 v219, v48, v49
	s_nop 1
	v_mfma_f32_32x32x16_bf16 v[66:81], v[224:227], v[216:219], v[66:81]
	v_lshl_or_b32 v128, v128, 5, v138
	s_cmp_gt_u32 s45, 3
	s_cselect_b64 s[62:63], -1, 0
	s_cmp_lt_u32 s45, 4
	v_mad_u64_u32 v[128:129], s[42:43], v128, s33, v[84:85]
	s_cbranch_scc1 .LBB0_906
	ds_read_u16 v129, v128
	s_waitcnt lgkmcnt(0)
	v_lshlrev_b32_e32 v129, 16, v129
	s_nop 2
	v_add_f32_e32 v66, v66, v129
